# P1 f32 row loop software-pipelined by one row on top of the nt hints and batched residual epilogues
# speedup vs baseline: 1.0470x; 1.0020x over previous
; #define GAS __attribute__((address_space(1)))
; #define LAS __attribute__((address_space(3)))
;     ...
;     __syncthreads();
;     bf16* XN = (bf16*)(F.ws + WS_XN);
;     const int gw = F.vcu * NWAVES + F.wave, NGW = F.G * NWAVES;
;     for (int m = gw; m < nrows; m += NGW) {
;         const float* xrow = m < ML ? src_lat + (size_t)m * DM : src_ctx + (size_t)(m - ML) * DM;
;         const int cnd = m < SEQ ? 0 : (m < ML ? 1 : 2);
;         const GAS f32x4* xr = (const GAS f32x4*)xrow + F.lane;
;     ...
;         for (int j = 0; j < 4; ++j) { const int col = 4 * F.lane + 256 * j;
;             const f32x4 g = *(const LAS f32x4*)(gl + col), sc = *(const LAS f32x4*)(scl + cnd * 1024 + col), sh = *(const LAS f32x4*)(shl + cnd * 1024 + col);
.LBB0_1119:
	s_or_b64 exec, exec, s[0:1]
	v_readlane_b32 s0, v243, 20
	s_lshl_b32 s0, s0, 3
	v_readlane_b32 s1, v243, 24
	s_add_i32 s0, s0, s1
	s_cmpk_gt_i32 s0, 0x41ff
	s_waitcnt lgkmcnt(0)
	s_barrier
	s_cbranch_scc1 .LBB0_1124
	v_lshlrev_b32_e32 v0, 4, v172
	v_add_u32_e32 v38, 0, v0
	v_readlane_b32 s1, v243, 18
	ds_read_b128 v[2:5], v38
	ds_read_b128 v[6:9], v38 offset:1024
	ds_read_b128 v[10:13], v38 offset:2048
	ds_read_b128 v[14:17], v38 offset:3072
	v_readlane_b32 s4, v243, 22
	s_lshl_b32 s2, s1, 3
	v_readlane_b32 s5, v243, 23
	s_ashr_i32 s1, s0, 31
	v_lshlrev_b32_e32 v18, 2, v172
	v_lshl_add_u64 v[34:35], s[4:5], 0, v[0:1]
	s_lshl_b64 s[4:5], s[0:1], 10
	s_add_u32 s4, s80, s4
	v_mov_b32_e32 v19, v1
	s_addc_u32 s5, s81, s5
	v_lshl_add_u64 v[18:19], s[4:5], 0, v[18:19]
	s_mov_b64 s[4:5], 0x3300000
	s_ashr_i32 s3, s2, 31
	v_lshl_add_u64 v[36:37], v[18:19], 0, s[4:5]
	s_lshl_b64 s[6:7], s[2:3], 10
	v_lshlrev_b32_e32 v0, 4, v172
	s_add_i32 s28, s0, 0xffffc000
	s_cmpk_lt_i32 s0, 0x4000
	v_readlane_b32 s24, v243, 27
	v_readlane_b32 s30, v243, 25
	v_readlane_b32 s25, v243, 28
	v_readlane_b32 s31, v243, 26
	s_cselect_b32 s25, s25, s31
	s_cselect_b32 s24, s24, s30
	s_cselect_b32 s29, s1, 0
	s_cselect_b32 s28, s0, s28
	s_lshl_b64 s[28:29], s[28:29], 12
	s_add_u32 s28, s24, s28
	s_addc_u32 s29, s25, s29
	global_load_dwordx4 v[232:235], v0, s[28:29] nt
	global_load_dwordx4 v[228:231], v0, s[28:29] offset:1024 nt
	global_load_dwordx4 v[224:227], v0, s[28:29] offset:2048 nt
	global_load_dwordx4 v[220:223], v0, s[28:29] offset:3072 nt
	s_waitcnt vmcnt(0)
	s_branch .LBB0_1122

; #define GAS __attribute__((address_space(1)))
;     ...
;     for (int m = gw; m < nrows; m += NGW) {
;         const float* xrow = m < ML ? src_lat + (size_t)m * DM : src_ctx + (size_t)(m - ML) * DM;
;         const int cnd = m < SEQ ? 0 : (m < ML ? 1 : 2);
;         const GAS f32x4* xr = (const GAS f32x4*)xrow + F.lane;
;         f32x4 v[4]; float s = 0.f;
;         if (lat_bf16 && m < ML) {
;             const GAS v2u* xb = (const GAS v2u*)((const bf16*)src_lat + (size_t)m * DM) + F.lane;
;             v2u w[4];
; #pragma unroll
;             for (int j = 0; j < 4; ++j) w[j] = xb[64 * j];
; #pragma unroll
;             for (int j = 0; j < 4; ++j) v[j] = f32x4{bflo(w[j].x), bfhi(w[j].x), bflo(w[j].y), bfhi(w[j].y)};
;         } else {
; #pragma unroll
;             for (int j = 0; j < 4; ++j) v[j] = xr[64 * j];
;         }
;         if (nparts > 0 && m >= ML) {
;             for (int p = 0; p < nparts; p += 4) {
;                 const GAS f32x4* pr = (const GAS f32x4*)(parts + (size_t)p * (512 * 1024) + (size_t)(m - ML) * DM) + F.lane;
;                 f32x4 w[4][4];
; #pragma unroll
;                 for (int q = 0; q < 4; ++q)
; #pragma unroll
;                     for (int j = 0; j < 4; ++j) w[q][j] = pr[(size_t)q * (512 * 1024 / 4) + 64 * j];
; #pragma unroll
;                 for (int j = 0; j < 4; ++j) v[j] += (w[0][j] + w[1][j]) + (w[2][j] + w[3][j]); }
;             GAS f32x4* cr = (GAS f32x4*)((float*)(F.ws + WS_CTXRES) + (size_t)(m - ML) * DM) + F.lane;
; #pragma unroll
;             for (int j = 0; j < 4; ++j) cr[64 * j] = v[j];
;         }
; #pragma unroll
;         for (int j = 0; j < 4; ++j) s += (v[j].x * v[j].x + v[j].y * v[j].y) + (v[j].z * v[j].z + v[j].w * v[j].w);
;         const float rstd = 1.f / sqrtf(wave_sum(s, F.lane) * (1.f / DM) + NORM_EPS);
.LBB0_1122:
	v_readlane_b32 s4, v243, 9
	s_add_i32 s12, s0, 0xffffc000
	v_readlane_b32 s5, v243, 10
	s_cmpk_lt_i32 s0, 0x4000
	s_mov_b32 s13, s5
	s_cselect_b64 s[4:5], -1, 0
	v_readlane_b32 s8, v243, 27
	v_readlane_b32 s14, v243, 25
	s_and_b64 vcc, s[4:5], exec
	v_readlane_b32 s9, v243, 28
	v_readlane_b32 s15, v243, 26
	s_cselect_b32 s10, s9, s15
	s_cselect_b32 s11, s8, s14
	s_cselect_b32 s9, s1, 0
	v_writelane_b32 v243, s12, 9
	s_cselect_b32 s8, s0, s12
	s_lshl_b64 s[8:9], s[8:9], 12
	s_add_u32 s8, s11, s8
	s_addc_u32 s9, s10, s9
	s_waitcnt vmcnt(4)
	v_mov_b64_e32 v[30:31], v[232:233]
	v_mov_b64_e32 v[32:33], v[234:235]
	v_mov_b64_e32 v[26:27], v[228:229]
	v_mov_b64_e32 v[28:29], v[230:231]
	v_mov_b64_e32 v[22:23], v[224:225]
	v_mov_b64_e32 v[24:25], v[226:227]
	v_mov_b64_e32 v[18:19], v[220:221]
	v_mov_b64_e32 v[20:21], v[222:223]
	s_add_u32 s22, s0, s2
	s_addc_u32 s23, s1, s3
	s_cmpk_lt_i32 s22, 0x4200
	s_cbranch_scc0 .Lp1_nopf
	s_add_i32 s28, s22, 0xffffc000
	s_cmpk_lt_i32 s22, 0x4000
	v_readlane_b32 s24, v243, 27
	v_readlane_b32 s30, v243, 25
	v_readlane_b32 s25, v243, 28
	v_readlane_b32 s31, v243, 26
	s_cselect_b32 s25, s25, s31
	s_cselect_b32 s24, s24, s30
	s_cselect_b32 s29, s23, 0
	s_cselect_b32 s28, s22, s28
	s_lshl_b64 s[28:29], s[28:29], 12
	s_add_u32 s28, s24, s28
	s_addc_u32 s29, s25, s29
	global_load_dwordx4 v[232:235], v0, s[28:29] nt
	global_load_dwordx4 v[228:231], v0, s[28:29] offset:1024 nt
	global_load_dwordx4 v[224:227], v0, s[28:29] offset:2048 nt
	global_load_dwordx4 v[220:223], v0, s[28:29] offset:3072 nt
.Lp1_nopf:
	v_writelane_b32 v243, s13, 10
	v_mul_f32_e32 v39, v31, v31
	v_mul_f32_e32 v40, v33, v33
	v_mul_f32_e32 v41, v27, v27
	v_mul_f32_e32 v42, v29, v29
	v_mul_f32_e32 v43, v23, v23
	v_mul_f32_e32 v44, v25, v25
	v_fmac_f32_e32 v39, v30, v30
	v_fmac_f32_e32 v40, v32, v32
	v_fmac_f32_e32 v41, v26, v26
	v_fmac_f32_e32 v42, v28, v28
	v_mul_f32_e32 v45, v19, v19
	v_mul_f32_e32 v46, v21, v21
	v_fmac_f32_e32 v43, v22, v22
	v_fmac_f32_e32 v44, v24, v24
	v_add_f32_e32 v39, v39, v40
	v_add_f32_e32 v40, v41, v42
	v_fmac_f32_e32 v45, v18, v18
	v_fmac_f32_e32 v46, v20, v20
	v_add_f32_e32 v41, v43, v44
	v_add_f32_e32 v39, v39, v40
	v_add_f32_e32 v42, v45, v46
	v_add_f32_e32 v39, v39, v41
	v_add_f32_e32 v39, v39, v42
	s_nop 1
	v_add_f32_dpp v39, v39, v39 row_ror:8 row_mask:0xf bank_mask:0xf bound_ctrl:1
	s_nop 1
	v_add_f32_dpp v39, v39, v39 row_ror:4 row_mask:0xf bank_mask:0xf bound_ctrl:1
	s_nop 1
	v_add_f32_dpp v39, v39, v39 row_ror:2 row_mask:0xf bank_mask:0xf bound_ctrl:1
	s_nop 1
	v_add_f32_dpp v39, v39, v39 row_ror:1 row_mask:0xf bank_mask:0xf bound_ctrl:1
	s_nop 0
	v_readlane_b32 s8, v39, 0
	v_readlane_b32 s10, v39, 16
	v_readlane_b32 s9, v39, 32
	v_readlane_b32 s11, v39, 48
	s_cbranch_vccnz .LBB0_1121
	v_readlane_b32 s12, v243, 9
	v_readlane_b32 s13, v243, 10
	s_lshl_b64 s[12:13], s[12:13], 12
	s_nop 0
	v_lshl_add_u64 v[40:41], v[34:35], 0, s[12:13]
	global_store_dwordx4 v[40:41], v[30:33], off
	global_store_dwordx4 v[40:41], v[26:29], off offset:1024
	global_store_dwordx4 v[40:41], v[22:25], off offset:2048
	global_store_dwordx4 v[40:41], v[18:21], off offset:3072
	s_branch .LBB0_1121
